# v11 + ffn gate/up weight 16-col groups permuted in prep so the silu epilogue stores 64-byte row segments (same math, same act layout)
# speedup vs baseline: 1.0072x; 1.0064x over previous
; __device__ __forceinline__ unsigned pk2(float lo, float hi) { const f32x2v v = {lo, hi}; const bf16x2v r = __builtin_convertvector(v, bf16x2v); return __builtin_bit_cast(unsigned, r); }
; __device__ __forceinline__ float silu_f(float x) { return x * __builtin_amdgcn_rcpf(1.f + __expf(-x)); }
; #define GEMM_EPI_LOOP _Pragma("unroll") for (int ai = 0; ai < 2; ++ai) _Pragma("unroll") for (int m = 0; m < 4; ++m) _Pragma("unroll") for (int bj = 0; bj < 2; ++bj)
; __device__ __forceinline__ void gemm_up_phase(const bf16_t* a, const bf16_t* wgu, bf16_t* act, char* lds) {
;     ...
;     GEMM_EPI_LOOP {
;       const int row = tm * 256 + ai * 128 + wr * 64 + m * 16 + fr;
;       const int col = tn * 128 + bj * 64 + wc * 16 + 4 * fq;
;       const f32x4 g = acc[ai][bj][m][0], u = acc[ai][bj][m][1];
;       u32x2 o; o.x = pk2(silu_f(g[0]) * u[0], silu_f(g[1]) * u[1]); o.y = pk2(silu_f(g[2]) * u[2], silu_f(g[3]) * u[3]);
;       *(u32x2*)(act + (size_t)row * DFF + col) = o;
;     }
.LBB0_645:
	v_mov_b32 v129, v179
	s_lshl_b32 s1, s34, 8
	v_ashrrev_i32_e32 v128, 2, v129
	v_and_b32_e32 v128, 0xffffffc0, v128
	v_and_or_b32 v130, v129, 15, s1
	s_lshl_b32 s0, s0, 7
	v_lshrrev_b32_e32 v129, 2, v129
	v_add_u32_e32 v128, v130, v128
	v_lshrrev_b32_e32 v131, 1, v179
	v_and_b32_e32 v131, 0x60, v131
	v_and_or_b32 v130, v129, 8, s0
	v_or_b32_e32 v130, v130, v131
	v_and_b32_e32 v131, 16, v179
	v_or_b32_e32 v130, v130, v131
	v_mul_f32_e32 v129, 0xbfb8aa3b, v124
	v_exp_f32_e32 v129, v129
	v_ashrrev_i32_e32 v131, 31, v130
	s_andn2_b64 vcc, exec, s[38:39]
	s_mov_b32 s34, s36
	v_add_f32_e32 v129, 1.0, v129
	v_rcp_f32_e32 v132, v129
	v_mul_f32_e32 v129, 0xbfb8aa3b, v125
	v_exp_f32_e32 v129, v129
	s_nop 0
	v_add_f32_e32 v129, 1.0, v129
	v_rcp_f32_e32 v133, v129
	s_nop 0
	v_pk_mul_f32 v[124:125], v[124:125], v[132:133]
	s_nop 0
	v_pk_mul_f32 v[120:121], v[120:121], v[124:125]
	s_nop 0
	v_cvt_pk_bf16_f32 v124, v120, v121
	v_mul_f32_e32 v120, 0xbfb8aa3b, v126
	v_mul_f32_e32 v121, 0xbfb8aa3b, v127
	v_exp_f32_e32 v120, v120
	v_exp_f32_e32 v121, v121
	v_add_f32_e32 v120, 1.0, v120
	v_add_f32_e32 v121, 1.0, v121
	v_rcp_f32_e32 v120, v120
	v_rcp_f32_e32 v121, v121
	s_nop 0
	v_pk_mul_f32 v[120:121], v[126:127], v[120:121]
	s_nop 0
	v_pk_mul_f32 v[120:121], v[122:123], v[120:121]
	v_lshlrev_b64 v[122:123], 1, v[130:131]
	v_cvt_pk_bf16_f32 v125, v120, v121
	v_mov_b64_e32 v[120:121], s[84:85]
	v_mad_i64_i32 v[126:127], s[0:1], v128, s3, v[120:121]
	v_lshl_add_u64 v[126:127], v[126:127], 0, v[122:123]
	v_mov_b32_e32 v140, v124
	v_mov_b32_e32 v141, v125
	v_mul_f32_e32 v124, 0xbfb8aa3b, v116
	v_mul_f32_e32 v125, 0xbfb8aa3b, v117
	v_exp_f32_e32 v124, v124
	v_exp_f32_e32 v125, v125
	v_add_f32_e32 v124, 1.0, v124
	v_add_f32_e32 v125, 1.0, v125
	v_rcp_f32_e32 v124, v124
	v_rcp_f32_e32 v125, v125
	s_nop 0
	v_pk_mul_f32 v[116:117], v[116:117], v[124:125]
	s_nop 0
	v_pk_mul_f32 v[112:113], v[112:113], v[116:117]
	s_nop 0
	v_cvt_pk_bf16_f32 v112, v112, v113
	v_mul_f32_e32 v113, 0xbfb8aa3b, v118
	v_exp_f32_e32 v113, v113
	s_nop 0
	v_add_f32_e32 v113, 1.0, v113
	v_rcp_f32_e32 v116, v113
	v_mul_f32_e32 v113, 0xbfb8aa3b, v119
	v_exp_f32_e32 v113, v113
	s_nop 0
	v_add_f32_e32 v113, 1.0, v113
	v_rcp_f32_e32 v117, v113
	s_nop 0
	v_pk_mul_f32 v[116:117], v[118:119], v[116:117]
	s_nop 0
	v_pk_mul_f32 v[114:115], v[114:115], v[116:117]
	s_nop 0
	v_cvt_pk_bf16_f32 v113, v114, v115
	v_mov_b32_e32 v142, v112
	v_mov_b32_e32 v143, v113
	s_nop 1
	v_permlane16_swap_b32_e32 v140, v142
	v_permlane16_swap_b32_e32 v141, v143
	global_store_dwordx4 v[126:127], v[140:143], off
	v_mul_f32_e32 v112, 0xbfb8aa3b, v108
	v_mul_f32_e32 v113, 0xbfb8aa3b, v109
	v_exp_f32_e32 v112, v112
	v_exp_f32_e32 v113, v113
	v_or_b32_e32 v114, 16, v128
	v_add_f32_e32 v112, 1.0, v112
	v_add_f32_e32 v113, 1.0, v113
	v_rcp_f32_e32 v112, v112
	v_rcp_f32_e32 v113, v113
	s_nop 0
	v_pk_mul_f32 v[108:109], v[108:109], v[112:113]
	s_nop 0
	v_pk_mul_f32 v[104:105], v[104:105], v[108:109]
	s_nop 0
	v_cvt_pk_bf16_f32 v104, v104, v105
	v_mul_f32_e32 v105, 0xbfb8aa3b, v110
	v_exp_f32_e32 v105, v105
	s_nop 0
	v_add_f32_e32 v105, 1.0, v105
	v_rcp_f32_e32 v108, v105
	v_mul_f32_e32 v105, 0xbfb8aa3b, v111
	v_exp_f32_e32 v105, v105
	s_nop 0
	v_add_f32_e32 v105, 1.0, v105
	v_rcp_f32_e32 v109, v105
	s_nop 0
	v_pk_mul_f32 v[108:109], v[110:111], v[108:109]
	s_nop 0
	v_pk_mul_f32 v[106:107], v[106:107], v[108:109]
	s_nop 0
	v_cvt_pk_bf16_f32 v105, v106, v107
	v_mad_i64_i32 v[106:107], s[0:1], v114, s3, v[120:121]
	v_lshl_add_u64 v[106:107], v[106:107], 0, v[122:123]
	v_mov_b32_e32 v144, v104
	v_mov_b32_e32 v145, v105
	v_mul_f32_e32 v104, 0xbfb8aa3b, v100
	v_mul_f32_e32 v105, 0xbfb8aa3b, v101
	v_exp_f32_e32 v104, v104
	v_exp_f32_e32 v105, v105
	v_add_f32_e32 v104, 1.0, v104
	v_add_f32_e32 v105, 1.0, v105
	v_rcp_f32_e32 v104, v104
	v_rcp_f32_e32 v105, v105
	s_nop 0
	v_pk_mul_f32 v[100:101], v[100:101], v[104:105]
	s_nop 0
	v_pk_mul_f32 v[96:97], v[96:97], v[100:101]
	s_nop 0
	v_cvt_pk_bf16_f32 v96, v96, v97
	v_mul_f32_e32 v97, 0xbfb8aa3b, v102
	v_exp_f32_e32 v97, v97
	s_nop 0
	v_add_f32_e32 v97, 1.0, v97
	v_rcp_f32_e32 v100, v97
	v_mul_f32_e32 v97, 0xbfb8aa3b, v103
	v_exp_f32_e32 v97, v97
	s_nop 0
	v_add_f32_e32 v97, 1.0, v97
	v_rcp_f32_e32 v101, v97
	s_nop 0
	v_pk_mul_f32 v[100:101], v[102:103], v[100:101]
	s_nop 0
	v_pk_mul_f32 v[98:99], v[98:99], v[100:101]
	s_nop 0
	v_cvt_pk_bf16_f32 v97, v98, v99
	v_mov_b32_e32 v146, v96
	v_mov_b32_e32 v147, v97
	s_nop 1
	v_permlane16_swap_b32_e32 v144, v146
	v_permlane16_swap_b32_e32 v145, v147
	global_store_dwordx4 v[106:107], v[144:147], off
	v_mul_f32_e32 v96, 0xbfb8aa3b, v92
	v_mul_f32_e32 v97, 0xbfb8aa3b, v93
	v_exp_f32_e32 v96, v96
	v_exp_f32_e32 v97, v97
	v_or_b32_e32 v98, 32, v128
	v_add_f32_e32 v96, 1.0, v96
	v_add_f32_e32 v97, 1.0, v97
	v_rcp_f32_e32 v96, v96
	v_rcp_f32_e32 v97, v97
	s_nop 0
	v_pk_mul_f32 v[92:93], v[92:93], v[96:97]
	s_nop 0
	v_pk_mul_f32 v[88:89], v[88:89], v[92:93]
	s_nop 0
	v_cvt_pk_bf16_f32 v88, v88, v89
	v_mul_f32_e32 v89, 0xbfb8aa3b, v94
	v_exp_f32_e32 v89, v89
	s_nop 0
	v_add_f32_e32 v89, 1.0, v89
	v_rcp_f32_e32 v92, v89
	v_mul_f32_e32 v89, 0xbfb8aa3b, v95
	v_exp_f32_e32 v89, v89
	s_nop 0
	v_add_f32_e32 v89, 1.0, v89
	v_rcp_f32_e32 v93, v89
	s_nop 0
	v_pk_mul_f32 v[92:93], v[94:95], v[92:93]
	s_nop 0
	v_pk_mul_f32 v[90:91], v[90:91], v[92:93]
	s_nop 0
	v_cvt_pk_bf16_f32 v89, v90, v91
	v_mad_i64_i32 v[90:91], s[0:1], v98, s3, v[120:121]
	v_lshl_add_u64 v[90:91], v[90:91], 0, v[122:123]
	v_mov_b32_e32 v148, v88
	v_mov_b32_e32 v149, v89
	v_mul_f32_e32 v88, 0xbfb8aa3b, v84
	v_mul_f32_e32 v89, 0xbfb8aa3b, v85
	v_exp_f32_e32 v88, v88
	v_exp_f32_e32 v89, v89
; __device__ __forceinline__ unsigned pk2(float lo, float hi) { const f32x2v v = {lo, hi}; const bf16x2v r = __builtin_convertvector(v, bf16x2v); return __builtin_bit_cast(unsigned, r); }
; __device__ __forceinline__ float silu_f(float x) { return x * __builtin_amdgcn_rcpf(1.f + __expf(-x)); }
; #define GEMM_EPI_LOOP _Pragma("unroll") for (int ai = 0; ai < 2; ++ai) _Pragma("unroll") for (int m = 0; m < 4; ++m) _Pragma("unroll") for (int bj = 0; bj < 2; ++bj)
; __device__ __forceinline__ void gemm_up_phase(const bf16_t* a, const bf16_t* wgu, bf16_t* act, char* lds) {
;     ...
;     GEMM_EPI_LOOP {
;       const int row = tm * 256 + ai * 128 + wr * 64 + m * 16 + fr;
;       const int col = tn * 128 + bj * 64 + wc * 16 + 4 * fq;
;       const f32x4 g = acc[ai][bj][m][0], u = acc[ai][bj][m][1];
;       u32x2 o; o.x = pk2(silu_f(g[0]) * u[0], silu_f(g[1]) * u[1]); o.y = pk2(silu_f(g[2]) * u[2], silu_f(g[3]) * u[3]);
;       *(u32x2*)(act + (size_t)row * DFF + col) = o;
;     }
	v_add_f32_e32 v88, 1.0, v88
	v_add_f32_e32 v89, 1.0, v89
	v_rcp_f32_e32 v88, v88
	v_rcp_f32_e32 v89, v89
	s_nop 0
	v_pk_mul_f32 v[84:85], v[84:85], v[88:89]
	s_nop 0
	v_pk_mul_f32 v[80:81], v[80:81], v[84:85]
	s_nop 0
	v_cvt_pk_bf16_f32 v80, v80, v81
	v_mul_f32_e32 v81, 0xbfb8aa3b, v86
	v_exp_f32_e32 v81, v81
	s_nop 0
	v_add_f32_e32 v81, 1.0, v81
	v_rcp_f32_e32 v84, v81
	v_mul_f32_e32 v81, 0xbfb8aa3b, v87
	v_exp_f32_e32 v81, v81
	s_nop 0
	v_add_f32_e32 v81, 1.0, v81
	v_rcp_f32_e32 v85, v81
	s_nop 0
	v_pk_mul_f32 v[84:85], v[86:87], v[84:85]
	s_nop 0
	v_pk_mul_f32 v[82:83], v[82:83], v[84:85]
	s_nop 0
	v_cvt_pk_bf16_f32 v81, v82, v83
	v_mov_b32_e32 v150, v80
	v_mov_b32_e32 v151, v81
	s_nop 1
	v_permlane16_swap_b32_e32 v148, v150
	v_permlane16_swap_b32_e32 v149, v151
	global_store_dwordx4 v[90:91], v[148:151], off
	v_mul_f32_e32 v80, 0xbfb8aa3b, v76
	v_mul_f32_e32 v81, 0xbfb8aa3b, v77
	v_exp_f32_e32 v80, v80
	v_exp_f32_e32 v81, v81
	v_or_b32_e32 v82, 48, v128
	v_add_f32_e32 v80, 1.0, v80
	v_add_f32_e32 v81, 1.0, v81
	v_rcp_f32_e32 v80, v80
	v_rcp_f32_e32 v81, v81
	s_nop 0
	v_pk_mul_f32 v[76:77], v[76:77], v[80:81]
	s_nop 0
	v_pk_mul_f32 v[72:73], v[72:73], v[76:77]
	s_nop 0
	v_cvt_pk_bf16_f32 v72, v72, v73
	v_mul_f32_e32 v73, 0xbfb8aa3b, v78
	v_exp_f32_e32 v73, v73
	s_nop 0
	v_add_f32_e32 v73, 1.0, v73
	v_rcp_f32_e32 v76, v73
	v_mul_f32_e32 v73, 0xbfb8aa3b, v79
	v_exp_f32_e32 v73, v73
	s_nop 0
	v_add_f32_e32 v73, 1.0, v73
	v_rcp_f32_e32 v77, v73
	s_nop 0
	v_pk_mul_f32 v[76:77], v[78:79], v[76:77]
	s_nop 0
	v_pk_mul_f32 v[74:75], v[74:75], v[76:77]
	s_nop 0
	v_cvt_pk_bf16_f32 v73, v74, v75
	v_mad_i64_i32 v[74:75], s[0:1], v82, s3, v[120:121]
	v_lshl_add_u64 v[74:75], v[74:75], 0, v[122:123]
	v_mov_b32_e32 v152, v72
	v_mov_b32_e32 v153, v73
	v_mul_f32_e32 v72, 0xbfb8aa3b, v68
	v_mul_f32_e32 v73, 0xbfb8aa3b, v69
	v_exp_f32_e32 v72, v72
	v_exp_f32_e32 v73, v73
	v_add_f32_e32 v72, 1.0, v72
	v_add_f32_e32 v73, 1.0, v73
	v_rcp_f32_e32 v72, v72
	v_rcp_f32_e32 v73, v73
	s_nop 0
	v_pk_mul_f32 v[68:69], v[68:69], v[72:73]
	s_nop 0
	v_pk_mul_f32 v[64:65], v[64:65], v[68:69]
	s_nop 0
	v_cvt_pk_bf16_f32 v64, v64, v65
	v_mul_f32_e32 v65, 0xbfb8aa3b, v70
	v_exp_f32_e32 v65, v65
	s_nop 0
	v_add_f32_e32 v65, 1.0, v65
	v_rcp_f32_e32 v68, v65
	v_mul_f32_e32 v65, 0xbfb8aa3b, v71
	v_exp_f32_e32 v65, v65
	s_nop 0
	v_add_f32_e32 v65, 1.0, v65
	v_rcp_f32_e32 v69, v65
	s_nop 0
	v_pk_mul_f32 v[68:69], v[70:71], v[68:69]
	s_nop 0
	v_pk_mul_f32 v[66:67], v[66:67], v[68:69]
	s_nop 0
	v_cvt_pk_bf16_f32 v65, v66, v67
	v_mov_b32_e32 v154, v64
	v_mov_b32_e32 v155, v65
	s_nop 1
	v_permlane16_swap_b32_e32 v152, v154
	v_permlane16_swap_b32_e32 v153, v155
	global_store_dwordx4 v[74:75], v[152:155], off
	v_mul_f32_e32 v64, 0xbfb8aa3b, v60
	v_mul_f32_e32 v65, 0xbfb8aa3b, v61
	v_exp_f32_e32 v64, v64
	v_exp_f32_e32 v65, v65
	v_add_u32_e32 v66, 0x80, v128
	v_add_f32_e32 v64, 1.0, v64
	v_add_f32_e32 v65, 1.0, v65
	v_rcp_f32_e32 v64, v64
	v_rcp_f32_e32 v65, v65
	s_nop 0
	v_pk_mul_f32 v[60:61], v[60:61], v[64:65]
	s_nop 0
	v_pk_mul_f32 v[56:57], v[56:57], v[60:61]
	s_nop 0
	v_cvt_pk_bf16_f32 v56, v56, v57
	v_mul_f32_e32 v57, 0xbfb8aa3b, v62
	v_exp_f32_e32 v57, v57
	s_nop 0
	v_add_f32_e32 v57, 1.0, v57
	v_rcp_f32_e32 v60, v57
	v_mul_f32_e32 v57, 0xbfb8aa3b, v63
	v_exp_f32_e32 v57, v57
	s_nop 0
	v_add_f32_e32 v57, 1.0, v57
	v_rcp_f32_e32 v61, v57
	s_nop 0
	v_pk_mul_f32 v[60:61], v[62:63], v[60:61]
	s_nop 0
	v_pk_mul_f32 v[58:59], v[58:59], v[60:61]
	s_nop 0
	v_cvt_pk_bf16_f32 v57, v58, v59
	v_mad_i64_i32 v[58:59], s[0:1], v66, s3, v[120:121]
	v_lshl_add_u64 v[58:59], v[58:59], 0, v[122:123]
	v_mov_b32_e32 v156, v56
	v_mov_b32_e32 v157, v57
	v_mul_f32_e32 v56, 0xbfb8aa3b, v52
	v_mul_f32_e32 v57, 0xbfb8aa3b, v53
	v_exp_f32_e32 v56, v56
	v_exp_f32_e32 v57, v57
	v_add_f32_e32 v56, 1.0, v56
	v_add_f32_e32 v57, 1.0, v57
	v_rcp_f32_e32 v56, v56
	v_rcp_f32_e32 v57, v57
	s_nop 0
	v_pk_mul_f32 v[52:53], v[52:53], v[56:57]
	s_nop 0
	v_pk_mul_f32 v[48:49], v[48:49], v[52:53]
	s_nop 0
	v_cvt_pk_bf16_f32 v48, v48, v49
	v_mul_f32_e32 v49, 0xbfb8aa3b, v54
	v_exp_f32_e32 v49, v49
	s_nop 0
	v_add_f32_e32 v49, 1.0, v49
	v_rcp_f32_e32 v52, v49
	v_mul_f32_e32 v49, 0xbfb8aa3b, v55
	v_exp_f32_e32 v49, v49
	s_nop 0
	v_add_f32_e32 v49, 1.0, v49
	v_rcp_f32_e32 v53, v49
	s_nop 0
	v_pk_mul_f32 v[52:53], v[54:55], v[52:53]
	s_nop 0
	v_pk_mul_f32 v[50:51], v[50:51], v[52:53]
	s_nop 0
	v_cvt_pk_bf16_f32 v49, v50, v51
	v_mov_b32_e32 v158, v48
	v_mov_b32_e32 v159, v49
	s_nop 1
	v_permlane16_swap_b32_e32 v156, v158
	v_permlane16_swap_b32_e32 v157, v159
	global_store_dwordx4 v[58:59], v[156:159], off
	v_mul_f32_e32 v48, 0xbfb8aa3b, v44
	v_mul_f32_e32 v49, 0xbfb8aa3b, v45
	v_exp_f32_e32 v48, v48
	v_exp_f32_e32 v49, v49
	v_add_u32_e32 v50, 0x90, v128
	v_add_f32_e32 v48, 1.0, v48
	v_add_f32_e32 v49, 1.0, v49
	v_rcp_f32_e32 v48, v48
	v_rcp_f32_e32 v49, v49
	s_nop 0
	v_pk_mul_f32 v[44:45], v[44:45], v[48:49]
	s_nop 0
	v_pk_mul_f32 v[40:41], v[40:41], v[44:45]
	s_nop 0
	v_cvt_pk_bf16_f32 v40, v40, v41
	v_mul_f32_e32 v41, 0xbfb8aa3b, v46
	v_exp_f32_e32 v41, v41
	s_nop 0
	v_add_f32_e32 v41, 1.0, v41
	v_rcp_f32_e32 v44, v41
; __device__ __forceinline__ unsigned pk2(float lo, float hi) { const f32x2v v = {lo, hi}; const bf16x2v r = __builtin_convertvector(v, bf16x2v); return __builtin_bit_cast(unsigned, r); }
; __device__ __forceinline__ float silu_f(float x) { return x * __builtin_amdgcn_rcpf(1.f + __expf(-x)); }
; #define GEMM_EPI_LOOP _Pragma("unroll") for (int ai = 0; ai < 2; ++ai) _Pragma("unroll") for (int m = 0; m < 4; ++m) _Pragma("unroll") for (int bj = 0; bj < 2; ++bj)
; __device__ __forceinline__ void gemm_up_phase(const bf16_t* a, const bf16_t* wgu, bf16_t* act, char* lds) {
;     ...
;     GEMM_EPI_LOOP {
;       const int row = tm * 256 + ai * 128 + wr * 64 + m * 16 + fr;
;       const int col = tn * 128 + bj * 64 + wc * 16 + 4 * fq;
;       const f32x4 g = acc[ai][bj][m][0], u = acc[ai][bj][m][1];
;       u32x2 o; o.x = pk2(silu_f(g[0]) * u[0], silu_f(g[1]) * u[1]); o.y = pk2(silu_f(g[2]) * u[2], silu_f(g[3]) * u[3]);
;       *(u32x2*)(act + (size_t)row * DFF + col) = o;
;     }
	v_mul_f32_e32 v41, 0xbfb8aa3b, v47
	v_exp_f32_e32 v41, v41
	s_nop 0
	v_add_f32_e32 v41, 1.0, v41
	v_rcp_f32_e32 v45, v41
	s_nop 0
	v_pk_mul_f32 v[44:45], v[46:47], v[44:45]
	s_nop 0
	v_pk_mul_f32 v[42:43], v[42:43], v[44:45]
	s_nop 0
	v_cvt_pk_bf16_f32 v41, v42, v43
	v_mad_i64_i32 v[42:43], s[0:1], v50, s3, v[120:121]
	v_lshl_add_u64 v[42:43], v[42:43], 0, v[122:123]
	v_mov_b32_e32 v160, v40
	v_mov_b32_e32 v161, v41
	v_mul_f32_e32 v40, 0xbfb8aa3b, v36
	v_mul_f32_e32 v41, 0xbfb8aa3b, v37
	v_exp_f32_e32 v40, v40
	v_exp_f32_e32 v41, v41
	v_add_f32_e32 v40, 1.0, v40
	v_add_f32_e32 v41, 1.0, v41
	v_rcp_f32_e32 v40, v40
	v_rcp_f32_e32 v41, v41
	s_nop 0
	v_pk_mul_f32 v[36:37], v[36:37], v[40:41]
	s_nop 0
	v_pk_mul_f32 v[32:33], v[32:33], v[36:37]
	s_nop 0
	v_cvt_pk_bf16_f32 v32, v32, v33
	v_mul_f32_e32 v33, 0xbfb8aa3b, v38
	v_exp_f32_e32 v33, v33
	s_nop 0
	v_add_f32_e32 v33, 1.0, v33
	v_rcp_f32_e32 v36, v33
	v_mul_f32_e32 v33, 0xbfb8aa3b, v39
	v_exp_f32_e32 v33, v33
	s_nop 0
	v_add_f32_e32 v33, 1.0, v33
	v_rcp_f32_e32 v37, v33
	s_nop 0
	v_pk_mul_f32 v[36:37], v[38:39], v[36:37]
	s_nop 0
	v_pk_mul_f32 v[34:35], v[34:35], v[36:37]
	s_nop 0
	v_cvt_pk_bf16_f32 v33, v34, v35
	v_mov_b32_e32 v162, v32
	v_mov_b32_e32 v163, v33
	s_nop 1
	v_permlane16_swap_b32_e32 v160, v162
	v_permlane16_swap_b32_e32 v161, v163
	global_store_dwordx4 v[42:43], v[160:163], off
	v_mul_f32_e32 v32, 0xbfb8aa3b, v28
	v_mul_f32_e32 v33, 0xbfb8aa3b, v29
	v_exp_f32_e32 v32, v32
	v_exp_f32_e32 v33, v33
	v_add_u32_e32 v34, 0xa0, v128
	v_add_f32_e32 v32, 1.0, v32
	v_add_f32_e32 v33, 1.0, v33
	v_rcp_f32_e32 v32, v32
	v_rcp_f32_e32 v33, v33
	s_nop 0
	v_pk_mul_f32 v[28:29], v[28:29], v[32:33]
	s_nop 0
	v_pk_mul_f32 v[24:25], v[24:25], v[28:29]
	s_nop 0
	v_cvt_pk_bf16_f32 v24, v24, v25
	v_mul_f32_e32 v25, 0xbfb8aa3b, v30
	v_exp_f32_e32 v25, v25
	s_nop 0
	v_add_f32_e32 v25, 1.0, v25
	v_rcp_f32_e32 v28, v25
	v_mul_f32_e32 v25, 0xbfb8aa3b, v31
	v_exp_f32_e32 v25, v25
	s_nop 0
	v_add_f32_e32 v25, 1.0, v25
	v_rcp_f32_e32 v29, v25
	s_nop 0
	v_pk_mul_f32 v[28:29], v[30:31], v[28:29]
	s_nop 0
	v_pk_mul_f32 v[26:27], v[26:27], v[28:29]
	s_nop 0
	v_cvt_pk_bf16_f32 v25, v26, v27
	v_mad_i64_i32 v[26:27], s[0:1], v34, s3, v[120:121]
	v_lshl_add_u64 v[26:27], v[26:27], 0, v[122:123]
	v_mov_b32_e32 v164, v24
	v_mov_b32_e32 v165, v25
	v_mul_f32_e32 v24, 0xbfb8aa3b, v20
	v_mul_f32_e32 v25, 0xbfb8aa3b, v21
	v_exp_f32_e32 v24, v24
	v_exp_f32_e32 v25, v25
	v_add_f32_e32 v24, 1.0, v24
	v_add_f32_e32 v25, 1.0, v25
	v_rcp_f32_e32 v24, v24
	v_rcp_f32_e32 v25, v25
	s_nop 0
	v_pk_mul_f32 v[20:21], v[20:21], v[24:25]
	s_nop 0
	v_pk_mul_f32 v[16:17], v[16:17], v[20:21]
	s_nop 0
	v_cvt_pk_bf16_f32 v16, v16, v17
	v_mul_f32_e32 v17, 0xbfb8aa3b, v22
	v_exp_f32_e32 v17, v17
	s_nop 0
	v_add_f32_e32 v17, 1.0, v17
	v_rcp_f32_e32 v20, v17
	v_mul_f32_e32 v17, 0xbfb8aa3b, v23
	v_exp_f32_e32 v17, v17
	s_nop 0
	v_add_f32_e32 v17, 1.0, v17
	v_rcp_f32_e32 v21, v17
	s_nop 0
	v_pk_mul_f32 v[20:21], v[22:23], v[20:21]
	s_nop 0
	v_pk_mul_f32 v[18:19], v[18:19], v[20:21]
	s_nop 0
	v_cvt_pk_bf16_f32 v17, v18, v19
	v_mov_b32_e32 v166, v16
	v_mov_b32_e32 v167, v17
	s_nop 1
	v_permlane16_swap_b32_e32 v164, v166
	v_permlane16_swap_b32_e32 v165, v167
	global_store_dwordx4 v[26:27], v[164:167], off
	v_mul_f32_e32 v16, 0xbfb8aa3b, v12
	v_mul_f32_e32 v17, 0xbfb8aa3b, v13
	v_exp_f32_e32 v16, v16
	v_exp_f32_e32 v17, v17
	v_add_u32_e32 v18, 0xb0, v128
	v_add_f32_e32 v16, 1.0, v16
	v_add_f32_e32 v17, 1.0, v17
	v_rcp_f32_e32 v16, v16
	v_rcp_f32_e32 v17, v17
	s_nop 0
	v_pk_mul_f32 v[12:13], v[12:13], v[16:17]
	s_nop 0
	v_pk_mul_f32 v[8:9], v[8:9], v[12:13]
	s_nop 0
	v_cvt_pk_bf16_f32 v8, v8, v9
	v_mul_f32_e32 v9, 0xbfb8aa3b, v14
	v_exp_f32_e32 v9, v9
	s_nop 0
	v_add_f32_e32 v9, 1.0, v9
	v_rcp_f32_e32 v12, v9
	v_mul_f32_e32 v9, 0xbfb8aa3b, v15
	v_exp_f32_e32 v9, v9
	s_nop 0
	v_add_f32_e32 v9, 1.0, v9
	v_rcp_f32_e32 v13, v9
	s_nop 0
	v_pk_mul_f32 v[12:13], v[14:15], v[12:13]
	s_nop 0
	v_pk_mul_f32 v[10:11], v[10:11], v[12:13]
	s_nop 0
	v_cvt_pk_bf16_f32 v9, v10, v11
	v_mad_i64_i32 v[10:11], s[0:1], v18, s3, v[120:121]
	v_lshl_add_u64 v[10:11], v[10:11], 0, v[122:123]
	v_mov_b32_e32 v168, v8
	v_mov_b32_e32 v169, v9
	v_mul_f32_e32 v8, 0xbfb8aa3b, v4
	v_mul_f32_e32 v9, 0xbfb8aa3b, v5
	v_exp_f32_e32 v8, v8
	v_exp_f32_e32 v9, v9
	s_mov_b32 s0, s30
	v_add_f32_e32 v8, 1.0, v8
	v_add_f32_e32 v9, 1.0, v9
	v_rcp_f32_e32 v8, v8
	v_rcp_f32_e32 v9, v9
	s_nop 0
	v_pk_mul_f32 v[4:5], v[4:5], v[8:9]
	s_nop 0
	v_pk_mul_f32 v[0:1], v[0:1], v[4:5]
	s_nop 0
	v_cvt_pk_bf16_f32 v0, v0, v1
	v_mul_f32_e32 v1, 0xbfb8aa3b, v6
	v_exp_f32_e32 v1, v1
	s_nop 0
	v_add_f32_e32 v1, 1.0, v1
	v_rcp_f32_e32 v4, v1
	v_mul_f32_e32 v1, 0xbfb8aa3b, v7
	v_exp_f32_e32 v1, v1
	s_nop 0
	v_add_f32_e32 v1, 1.0, v1
	v_rcp_f32_e32 v5, v1
	s_nop 0
	v_pk_mul_f32 v[4:5], v[6:7], v[4:5]
	s_nop 0
	v_pk_mul_f32 v[2:3], v[2:3], v[4:5]
	s_nop 0
	v_cvt_pk_bf16_f32 v1, v2, v3
	v_mov_b32_e32 v170, v0
	v_mov_b32_e32 v171, v1
	s_nop 1
	v_permlane16_swap_b32_e32 v168, v170
	v_permlane16_swap_b32_e32 v169, v171
	global_store_dwordx4 v[10:11], v[168:171], off
	s_nop 1
	s_cbranch_vccz .LBB0_660

; __device__ __forceinline__ unsigned pk2(float lo, float hi) { const f32x2v v = {lo, hi}; const bf16x2v r = __builtin_convertvector(v, bf16x2v); return __builtin_bit_cast(unsigned, r); }
; __device__ __forceinline__ void tr_cvt(const float* __restrict__ src, int N, int K, bf16_t* __restrict__ dst, int ldd, int rs, int ro, char* ldsc, int& rot) {
;     ...
;     for (int u = 0; u < 3; ++u)
; #pragma unroll
;       for (int ps = 0; ps < 4; ++ps) {
;         const int i = ps * 16 + (tid >> 4), j = (tid & 15) * 4;
;         float* d = lds + u * 4160 + i * 65 + j; d[0] = v[u][ps].x; d[1] = v[u][ps].y; d[2] = v[u][ps].z; d[3] = v[u][ps].w;
;       }
;     __syncthreads();
; #pragma unroll
;     for (int u = 0; u < 3; ++u) {
;       const int tile = t0 + hb * 3 + u, tk = tile / ntn, tn = tile - tk * ntn, k0 = tk * 64, n0 = tn * 64;
;       const int j = tid >> 2, kq = tid & 3, n = n0 + j;
;       if (tile < nt && n < N) {
;         const float* l = lds + u * 4160;
;         unsigned w[8];
; #pragma unroll
;         for (int q = 0; q < 8; ++q) w[q] = pk2(l[(kq * 16 + 2 * q) * 65 + j], l[(kq * 16 + 2 * q + 1) * 65 + j]);
;         bf16_t* o = dst + (size_t)((n >> 4) * rs + (n & 15) + ro) * ldd + k0 + kq * 16;
;         u32x4 w0, w1; w0.x = w[0]; w0.y = w[1]; w0.z = w[2]; w0.w = w[3]; w1.x = w[4]; w1.y = w[5]; w1.z = w[6]; w1.w = w[7];
;         *(u32x4*)o = w0; *(u32x4*)(o + 8) = w1;
.LBB0_692:
	s_or_b64 exec, exec, s[16:17]
	s_waitcnt vmcnt(0)
	ds_write2_b32 v61, v4, v5 offset1:1
	ds_write2_b32 v61, v6, v7 offset0:2 offset1:3
	v_add_u32_e32 v4, 0x1040, v61
	ds_write2_b32 v4, v0, v1 offset1:1
	v_add_u32_e32 v0, 0x1048, v61
	ds_write2_b32 v0, v2, v3 offset1:1
	v_add_u32_e32 v0, 0x2080, v61
	ds_write2_b32 v0, v12, v13 offset1:1
	v_add_u32_e32 v0, 0x2088, v61
	ds_write2_b32 v0, v14, v15 offset1:1
	v_add_u32_e32 v0, 0x30c0, v61
	ds_write2_b32 v0, v8, v9 offset1:1
	v_add_u32_e32 v0, 0x30c8, v61
	ds_write2_b32 v0, v10, v11 offset1:1
	v_add_u32_e32 v0, 0x4100, v61
	ds_write2_b32 v0, v20, v21 offset1:1
	v_add_u32_e32 v0, 0x4108, v61
	ds_write2_b32 v0, v22, v23 offset1:1
	v_add_u32_e32 v0, 0x5140, v61
	ds_write2_b32 v0, v16, v17 offset1:1
	v_add_u32_e32 v0, 0x5148, v61
	ds_write2_b32 v0, v18, v19 offset1:1
	v_add_u32_e32 v0, 0x6180, v61
	ds_write2_b32 v0, v28, v29 offset1:1
	v_add_u32_e32 v0, 0x6188, v61
	ds_write2_b32 v0, v30, v31 offset1:1
	v_add_u32_e32 v0, 0x71c0, v61
	ds_write2_b32 v0, v24, v25 offset1:1
	v_add_u32_e32 v0, 0x71c8, v61
	ds_write2_b32 v0, v26, v27 offset1:1
	v_add_u32_e32 v0, 0x8200, v61
	ds_write2_b32 v0, v36, v37 offset1:1
	v_add_u32_e32 v0, 0x8208, v61
	ds_write2_b32 v0, v38, v39 offset1:1
	v_add_u32_e32 v0, 0x9240, v61
	ds_write2_b32 v0, v32, v33 offset1:1
	v_add_u32_e32 v0, 0x9248, v61
	ds_write2_b32 v0, v34, v35 offset1:1
	v_add_u32_e32 v0, 0xa280, v61
	ds_write2_b32 v0, v44, v45 offset1:1
	v_add_u32_e32 v0, 0xa288, v61
	ds_write2_b32 v0, v46, v47 offset1:1
	v_add_u32_e32 v0, 0xb2c0, v61
	ds_write2_b32 v0, v40, v41 offset1:1
	v_add_u32_e32 v0, 0xb2c8, v61
	ds_write2_b32 v0, v42, v43 offset1:1
	v_add3_u32 v0, v66, v70, v72
	v_cmp_gt_i32_e64 s[0:1], s25, v0
	s_and_b64 s[16:17], vcc, s[0:1]
	v_lshlrev_b32_e32 v176, 1, v50
	s_waitcnt lgkmcnt(0)
	s_barrier
	s_and_saveexec_b64 s[0:1], s[16:17]
	s_cbranch_execz .LBB0_694
	ds_read2_b32 v[0:1], v62 offset1:65
	ds_read2_b32 v[2:3], v62 offset0:130 offset1:195
	v_add_u32_e32 v4, 0x400, v62
	v_add_u32_e32 v6, 0x800, v62
	v_add_u32_e32 v8, 0xc00, v62
	s_waitcnt lgkmcnt(1)
	v_cvt_pk_bf16_f32 v0, v0, v1
	s_waitcnt lgkmcnt(0)
	v_cvt_pk_bf16_f32 v1, v2, v3
	ds_read2_b32 v[2:3], v4 offset0:4 offset1:69
	ds_read2_b32 v[4:5], v4 offset0:134 offset1:199
	s_waitcnt lgkmcnt(1)
	v_cvt_pk_bf16_f32 v2, v2, v3
	s_waitcnt lgkmcnt(0)
	v_cvt_pk_bf16_f32 v3, v4, v5
	ds_read2_b32 v[4:5], v6 offset0:8 offset1:73
	ds_read2_b32 v[6:7], v6 offset0:138 offset1:203
	s_waitcnt lgkmcnt(1)
	v_cvt_pk_bf16_f32 v4, v4, v5
	s_waitcnt lgkmcnt(0)
	v_cvt_pk_bf16_f32 v5, v6, v7
	ds_read2_b32 v[6:7], v8 offset0:12 offset1:77
	ds_read2_b32 v[8:9], v8 offset0:142 offset1:207
	s_waitcnt lgkmcnt(1)
	v_cvt_pk_bf16_f32 v6, v6, v7
	s_waitcnt lgkmcnt(0)
	v_cvt_pk_bf16_f32 v7, v8, v9
	v_mul_lo_u32 v8, v53, s27
	v_add3_u32 v8, v64, v69, v8
	v_and_or_b32 v8, v8, s28, v60
	v_bfe_u32 v106, v8, 5, 3
	v_lshrrev_b32_e32 v107, 1, v106
	v_and_b32_e32 v106, 1, v106
	v_lshl_or_b32 v106, v106, 2, v107
	v_and_b32_e32 v8, 0xffffff1f, v8
	v_lshl_or_b32 v8, v106, 5, v8
	v_ashrrev_i32_e32 v9, 31, v8
	v_lshlrev_b64 v[8:9], 11, v[8:9]
	v_lshl_add_u64 v[8:9], s[30:31], 0, v[8:9]
	v_ashrrev_i32_e32 v53, 31, v52
	v_lshl_add_u64 v[8:9], v[52:53], 1, v[8:9]
	v_lshl_add_u64 v[8:9], v[8:9], 0, v[176:177]
	global_store_dwordx4 v[8:9], v[0:3], off
	global_store_dwordx4 v[8:9], v[4:7], off offset:16
; __device__ __forceinline__ unsigned pk2(float lo, float hi) { const f32x2v v = {lo, hi}; const bf16x2v r = __builtin_convertvector(v, bf16x2v); return __builtin_bit_cast(unsigned, r); }
; __device__ __forceinline__ void tr_cvt(const float* __restrict__ src, int N, int K, bf16_t* __restrict__ dst, int ldd, int rs, int ro, char* ldsc, int& rot) {
;     ...
;     for (int u = 0; u < 3; ++u) {
;       const int tile = t0 + hb * 3 + u, tk = tile / ntn, tn = tile - tk * ntn, k0 = tk * 64, n0 = tn * 64;
;       const int j = tid >> 2, kq = tid & 3, n = n0 + j;
;       if (tile < nt && n < N) {
;         const float* l = lds + u * 4160;
;         unsigned w[8];
; #pragma unroll
;         for (int q = 0; q < 8; ++q) w[q] = pk2(l[(kq * 16 + 2 * q) * 65 + j], l[(kq * 16 + 2 * q + 1) * 65 + j]);
;         bf16_t* o = dst + (size_t)((n >> 4) * rs + (n & 15) + ro) * ldd + k0 + kq * 16;
;         u32x4 w0, w1; w0.x = w[0]; w0.y = w[1]; w0.z = w[2]; w0.w = w[3]; w1.x = w[4]; w1.y = w[5]; w1.z = w[6]; w1.w = w[7];
;         *(u32x4*)o = w0; *(u32x4*)(o + 8) = w1;
.LBB0_694:
	s_or_b64 exec, exec, s[0:1]
	v_add_u32_e32 v0, v66, v67
	v_add3_u32 v1, v0, v73, 64
	v_cmp_gt_i32_e32 vcc, s25, v1
	s_and_b64 s[16:17], s[36:37], vcc
	s_and_saveexec_b64 s[0:1], s[16:17]
	s_cbranch_execz .LBB0_696
	v_add_u32_e32 v1, 0x4000, v62
	ds_read2_b32 v[2:3], v1 offset0:64 offset1:129
	v_add_u32_e32 v1, 0x4200, v62
	ds_read2_b32 v[4:5], v1 offset0:66 offset1:131
	v_add_u32_e32 v1, 0x4400, v62
	s_waitcnt lgkmcnt(1)
	v_cvt_pk_bf16_f32 v2, v2, v3
	s_waitcnt lgkmcnt(0)
	v_cvt_pk_bf16_f32 v3, v4, v5
	ds_read2_b32 v[4:5], v1 offset0:68 offset1:133
	v_add_u32_e32 v1, 0x4600, v62
	ds_read2_b32 v[6:7], v1 offset0:70 offset1:135
	v_add_u32_e32 v1, 0x4800, v62
	s_waitcnt lgkmcnt(1)
	v_cvt_pk_bf16_f32 v4, v4, v5
	s_waitcnt lgkmcnt(0)
	v_cvt_pk_bf16_f32 v5, v6, v7
	ds_read2_b32 v[6:7], v1 offset0:72 offset1:137
	v_add_u32_e32 v1, 0x4a00, v62
	ds_read2_b32 v[8:9], v1 offset0:74 offset1:139
	v_add_u32_e32 v1, 0x4c00, v62
	s_waitcnt lgkmcnt(1)
	v_cvt_pk_bf16_f32 v6, v6, v7
	s_waitcnt lgkmcnt(0)
	v_cvt_pk_bf16_f32 v7, v8, v9
	ds_read2_b32 v[8:9], v1 offset0:76 offset1:141
	v_add_u32_e32 v1, 0x4e00, v62
	ds_read2_b32 v[10:11], v1 offset0:78 offset1:143
	v_mul_lo_u32 v1, v55, s27
	v_add3_u32 v1, v64, v65, v1
	s_waitcnt lgkmcnt(1)
	v_cvt_pk_bf16_f32 v8, v8, v9
	v_ashrrev_i32_e32 v55, 31, v54
	s_waitcnt lgkmcnt(0)
	v_cvt_pk_bf16_f32 v9, v10, v11
	v_and_or_b32 v10, v1, s28, v60
	v_bfe_u32 v106, v10, 5, 3
	v_lshrrev_b32_e32 v107, 1, v106
	v_and_b32_e32 v106, 1, v106
	v_lshl_or_b32 v106, v106, 2, v107
	v_and_b32_e32 v10, 0xffffff1f, v10
	v_lshl_or_b32 v10, v106, 5, v10
	v_ashrrev_i32_e32 v11, 31, v10
	v_lshlrev_b64 v[10:11], 11, v[10:11]
	v_lshl_add_u64 v[10:11], s[30:31], 0, v[10:11]
	v_lshl_add_u64 v[10:11], v[54:55], 1, v[10:11]
	v_lshl_add_u64 v[10:11], v[10:11], 0, v[176:177]
	global_store_dwordx4 v[10:11], v[2:5], off
	global_store_dwordx4 v[10:11], v[6:9], off offset:16
.LBB0_696:
	s_or_b64 exec, exec, s[0:1]
	v_add3_u32 v0, v0, v74, s15
	v_cmp_gt_i32_e32 vcc, s25, v0
	s_and_b64 s[16:17], s[38:39], vcc
	s_and_saveexec_b64 s[0:1], s[16:17]
	s_cbranch_execz .LBB0_667
	v_add_u32_e32 v0, 0x8000, v62
	v_add_u32_e32 v4, 0x8400, v62
	ds_read2_b32 v[0:1], v0 offset0:128 offset1:193
	ds_read2_b32 v[2:3], v4 offset0:2 offset1:67
	v_add_u32_e32 v6, 0x8800, v62
	v_add_u32_e32 v8, 0x8c00, v62
	s_waitcnt lgkmcnt(1)
	v_cvt_pk_bf16_f32 v0, v0, v1
	s_waitcnt lgkmcnt(0)
	v_cvt_pk_bf16_f32 v1, v2, v3
	ds_read2_b32 v[2:3], v4 offset0:132 offset1:197
	ds_read2_b32 v[4:5], v6 offset0:6 offset1:71
	s_waitcnt lgkmcnt(1)
	v_cvt_pk_bf16_f32 v2, v2, v3
	s_waitcnt lgkmcnt(0)
	v_cvt_pk_bf16_f32 v3, v4, v5
	ds_read2_b32 v[4:5], v6 offset0:136 offset1:201
	ds_read2_b32 v[6:7], v8 offset0:10 offset1:75
	s_waitcnt lgkmcnt(1)
	v_cvt_pk_bf16_f32 v4, v4, v5
	s_waitcnt lgkmcnt(0)
	v_cvt_pk_bf16_f32 v5, v6, v7
	ds_read2_b32 v[6:7], v8 offset0:140 offset1:205
	s_waitcnt lgkmcnt(0)
	v_cvt_pk_bf16_f32 v6, v6, v7
	v_add_u32_e32 v7, 0x9000, v62
	ds_read2_b32 v[8:9], v7 offset0:14 offset1:79
	s_waitcnt lgkmcnt(0)
	v_cvt_pk_bf16_f32 v7, v8, v9
	v_mul_lo_u32 v8, v57, s27
	v_add_u32_e32 v9, v64, v65
	v_add3_u32 v8, v9, v8, s15
	v_and_or_b32 v8, v8, s28, v60
	v_bfe_u32 v106, v8, 5, 3
	v_lshrrev_b32_e32 v107, 1, v106
	v_and_b32_e32 v106, 1, v106
	v_lshl_or_b32 v106, v106, 2, v107
	v_and_b32_e32 v8, 0xffffff1f, v8
	v_lshl_or_b32 v8, v106, 5, v8
	v_ashrrev_i32_e32 v9, 31, v8
	v_lshlrev_b64 v[8:9], 11, v[8:9]
	v_lshl_add_u64 v[8:9], s[30:31], 0, v[8:9]
	v_ashrrev_i32_e32 v57, 31, v56
	v_lshl_add_u64 v[8:9], v[56:57], 1, v[8:9]
	v_lshl_add_u64 v[8:9], v[8:9], 0, v[176:177]
	global_store_dwordx4 v[8:9], v[0:3], off
	global_store_dwordx4 v[8:9], v[4:7], off offset:16
	s_branch .LBB0_667
